# P1 detour threshold 144 instead of 128 (workgroups >= 144 run the weight conversion before their in-proj GEMM unit)
# speedup vs baseline: 1.0161x; 1.0038x over previous
; #define LAS __attribute__((address_space(3)))
; __global__ void __launch_bounds__(512, 2) mk_fwd(Args a) {
;     ...
;             pg8::Gemm g{XN, WIN, DM, DM, DM, 0, 0}; pg8::StaticOrder S; S.init(NTOK, INW, G, bx);
;             LAS float* rsl = (LAS float*)(lds + 131072);
;             Unit u0, u1; int pm0 = 0;
;             pg8::RsPre pre{PART, rsl, 0, 0, 0};
;             if (S.next(0, u0)) { pm0 = u0.pm; const bool two = S.next(1, u1); pre.pm0 = u0.pm; pre.pm1 = two ? u1.pm : u0.pm; pre.ntab = two ? 2 : 1; }
;             EpiInProj E{rsl, pm0, (bf16_t*)(ws + WS_Q), (bf16_t*)(ws + WS_K), (bf16_t*)(ws + WS_V), UB};
;             pg8::gemm_phase<EpiInProj, pg8::StaticOrder, true, true, pg8::RsPre>(lds, g, S, E, pre);
.LBB0_161:
	v_readlane_b32 s0, v254, 53
	s_and_b32 s15, s0, 1
	s_add_u32 s54, s92, 0x3800000
	s_addc_u32 s55, s93, 0
	s_add_u32 s56, s92, 0x5800000
	s_addc_u32 s57, s93, 0
	s_add_u32 s44, s92, 0x7000000
	s_addc_u32 s45, s93, 0
	s_add_u32 s62, s92, 0xd800000
	s_addc_u32 s63, s93, 0
	s_cmp_eq_u32 s15, 0
	s_cselect_b64 s[64:65], -1, 0
	s_and_b64 vcc, exec, s[38:39]
	s_mov_b32 s18, s42
	v_readlane_b32 s1, v254, 54
	s_cbranch_vccnz .LBB0_307
	v_readlane_b32 vcc_lo, v255, 56
	s_cmp_lg_u32 vcc_lo, 0
	s_cbranch_scc1 .Ldt_cont
	s_cmpk_lt_i32 s49, 144
	s_cbranch_scc1 .Ldt_cont
	s_waitcnt lgkmcnt(0)
	v_writelane_b32 v255, 1, 56
	s_branch .LBB0_307
